# v16 + de-serialised f32-cache tile loads: band-sample loop keeps raw f32 prefetch in flight and converts at the LDS-store point; sample stick-breaking loop issues its 16 f32 loads back-to-back (one ex
# speedup vs baseline: 1.0115x; 1.0115x over previous
; template <int MODE> __device__ __forceinline__ void attn_unit(const AU& U, LAS unsigned char* lds, const float* rope, const float* biasg) {
;     ...
;     f32x16 o0, o1;
; #pragma unroll
;     for (int i = 0; i < 16; ++i) { o0[i] = 0.f; o1[i] = 0.f; }
;     float lrun = 0.f; bool fresh = true; f32x16 negm;
; #pragma unroll
;     for (int i = 0; i < 16; ++i) negm[i] = 0.f;
;     v4u preA[3], preB[3]; TL C; tile_ctx<MODE>(U, tid, C);
;     tile_loads<MODE>(U, C, glo, preA); tile_stores<MODE>(lds, C, preA);
;     tile_loads<MODE>(U, C, (glo < ghi ? glo + 1 : ghi), preA);
;     __syncthreads();
;     int cur = 0;
.LBB0_510:
	s_lshl_b32 s22, s16, 1
	s_add_u32 s8, s14, s22
	s_addc_u32 s9, s15, 0
	s_add_u32 s10, s8, 0xc40
	s_addc_u32 s11, s9, 0
	s_add_u32 s12, s8, 0x1040
	s_addc_u32 s13, s9, 0
	v_mov_b32_e32 v8, s13
	v_mov_b32_e32 v9, s11
	v_mov_b32_e32 v10, s12
	v_mov_b32_e32 v11, s10
	v_mad_i64_i32 v[4:5], s[8:9], v172, s54, v[16:17]
	v_cndmask_b32_e64 v7, v8, v9, s[6:7]
	v_cndmask_b32_e64 v6, v10, v11, s[6:7]
	v_lshl_add_u64 v[178:179], v[4:5], 1, v[6:7]
	v_mad_i64_i32 v[4:5], s[8:9], v170, s54, v[12:13]
	v_cndmask_b32_e64 v7, v8, v9, s[4:5]
	v_cndmask_b32_e64 v6, v10, v11, s[4:5]
	v_lshl_add_u64 v[180:181], v[4:5], 1, v[6:7]
	v_lshlrev_b32_e32 v171, 2, v24
	v_lshrrev_b32_e32 v4, 2, v14
	v_and_or_b32 v4, v4, 3, v171
	v_lshlrev_b32_e32 v5, 1, v14
	v_lshlrev_b32_e32 v6, 3, v14
	v_mul_u32_u24_e32 v4, 0xc0, v4
	v_and_b32_e32 v5, 32, v5
	v_and_b32_e32 v6, 24, v6
	v_or3_b32 v173, v4, v5, v6
	v_ashrrev_i32_e32 v5, 31, v2
	v_mov_b32_e32 v4, v2
	v_lshl_add_u64 v[182:183], v[2:3], 2, s[20:21]
	v_lshlrev_b32_e32 v2, 2, v15
	s_lshl_b32 s2, s2, 2
	s_addk_i32 s3, 0x200
	v_sub_u32_e32 v2, v168, v2
	s_and_b32 s2, s2, 0xffffff80
	s_ashr_i32 s23, s3, 6
	v_mov_b32_e32 v19, v3
	v_ashrrev_i32_e32 v7, 31, v18
	v_mov_b32_e32 v6, v18
	v_mul_i32_i24_e32 v8, -4, v24
	v_subrev_u32_e32 v2, s2, v2
	v_mov_b32_e32 v16, v3
	v_mov_b32_e32 v17, v3
	s_max_i32 s72, s23, 8
	v_mad_u32_u24 v215, v15, s53, v1
	v_lshl_add_u64 v[184:185], v[4:5], 2, s[18:19]
	v_lshl_add_u64 v[186:187], v[18:19], 2, s[20:21]
	v_lshl_add_u64 v[188:189], v[6:7], 2, s[18:19]
	v_add_u32_e32 v216, s55, v2
	v_add3_u32 v217, s3, v8, v15
	v_mov_b32_e32 v2, v3
	v_mov_b32_e32 v4, v3
	v_mov_b32_e32 v5, v3
	v_mov_b32_e32 v6, v3
	v_mov_b32_e32 v7, v3
	v_mov_b32_e32 v8, v3
	v_mov_b32_e32 v9, v3
	v_mov_b32_e32 v10, v3
	v_mov_b32_e32 v11, v3
	v_mov_b32_e32 v12, v3
	v_mov_b32_e32 v13, v3
	v_mov_b32_e32 v14, v3
	v_mov_b32_e32 v15, v3
	v_mov_b64_e32 v[32:33], v[16:17]
	v_mov_b64_e32 v[64:65], v[16:17]
	v_mov_b64_e32 v[48:49], v[16:17]
	s_add_i32 s72, s72, -8
	s_add_i32 s73, s23, -5
	s_add_i32 s76, s23, -3
	s_add_i32 s77, s23, -6
	s_add_i32 s80, s23, -4
	s_mov_b32 s2, 0
	v_mov_b32_e32 v219, 0
	s_mov_b64 s[8:9], -1
	v_mov_b64_e32 v[30:31], v[14:15]
	v_mov_b64_e32 v[28:29], v[12:13]
	v_mov_b64_e32 v[26:27], v[10:11]
	v_mov_b64_e32 v[24:25], v[8:9]
	v_mov_b64_e32 v[22:23], v[6:7]
	v_mov_b64_e32 v[20:21], v[4:5]
	v_mov_b64_e32 v[18:19], v[2:3]
	v_mov_b64_e32 v[62:63], v[14:15]
	v_mov_b64_e32 v[60:61], v[12:13]
	v_mov_b64_e32 v[58:59], v[10:11]
	v_mov_b64_e32 v[56:57], v[8:9]
	v_mov_b64_e32 v[54:55], v[6:7]
	v_mov_b64_e32 v[52:53], v[4:5]
	v_mov_b64_e32 v[50:51], v[2:3]
	v_mov_b64_e32 v[46:47], v[14:15]
	v_mov_b64_e32 v[44:45], v[12:13]
	v_mov_b64_e32 v[42:43], v[10:11]
	v_mov_b64_e32 v[40:41], v[8:9]
	v_mov_b64_e32 v[38:39], v[6:7]
	v_mov_b64_e32 v[36:37], v[4:5]
	v_mov_b64_e32 v[34:35], v[2:3]
	s_mov_b32 s98, 0
	s_mov_b32 s99, 0
	s_waitcnt lgkmcnt(0)
	s_barrier
	s_branch .LBB0_514

; #define LAS __attribute__((address_space(3)))
; __device__ __forceinline__ unsigned pk2(float lo, float hi) { f32x2_t v = {lo, hi}; bf16x2_t b = __builtin_convertvector(v, bf16x2_t); return __builtin_bit_cast(unsigned, b); }
; template <int MODE> __device__ __forceinline__ void tile_loads(const AU& U, const TL& C, int T, v4u (&pre)[3]) {
;     ...
;             const float* fs = cc < 8 ? U.kAf + (size_t)(T * 64 + row) * U.pA + cc * 8 : U.vAf + (size_t)(T * 64 + row) * U.pA + (cc - 8) * 8;
;             const f32x4 a = *(const f32x4*)fs, b = *(const f32x4*)(fs + 4); v4u o; o.x = pk2(a[0], a[1]); o.y = pk2(a[2], a[3]); o.z = pk2(b[0], b[1]); o.w = pk2(b[2], b[3]); pre[i] = o; }
; template <int MODE> __device__ __forceinline__ void tile_stores(LAS unsigned char* buf, const TL& C, const v4u (&pre)[3]) {
;     constexpr int NLD = ((MODE == 0 ? 20 : 16) * 64 + 511) / 512;
; #pragma unroll
;     for (int i = 0; i < NLD; ++i) *(LAS v4u*)(buf + C.ld[i]) = pre[i];
; }
.LBB0_512:
	s_cmp_eq_u32 s98, 0
	s_cbranch_scc1 .Lbs_a_ok
	s_waitcnt vmcnt(0)
	v_cvt_pk_bf16_f32 v4, v4, v5
	v_cvt_pk_bf16_f32 v5, v6, v7
	v_cvt_pk_bf16_f32 v6, v224, v225
	v_cvt_pk_bf16_f32 v7, v226, v227
	v_cvt_pk_bf16_f32 v8, v8, v9
	v_cvt_pk_bf16_f32 v9, v10, v11
	v_cvt_pk_bf16_f32 v10, v228, v229
	v_cvt_pk_bf16_f32 v11, v238, v239

; __device__ __forceinline__ unsigned pk2(float lo, float hi) { f32x2_t v = {lo, hi}; bf16x2_t b = __builtin_convertvector(v, bf16x2_t); return __builtin_bit_cast(unsigned, b); }
; template <int MODE> __device__ __forceinline__ void tile_loads(const AU& U, const TL& C, int T, v4u (&pre)[3]) {
;     constexpr int CPR = MODE == 0 ? 20 : 16, NCH = 64 * CPR, NLD = (NCH + 511) / 512;
;     const bool useA = T < U.ntA;
;     if (MODE != 0 && useA && U.kAf) {
; #pragma unroll
;         for (int i = 0; i < NLD; ++i) { const int row = C.c[i] / CPR, cc = C.c[i] % CPR;
;             const float* fs = cc < 8 ? U.kAf + (size_t)(T * 64 + row) * U.pA + cc * 8 : U.vAf + (size_t)(T * 64 + row) * U.pA + (cc - 8) * 8;
;             const f32x4 a = *(const f32x4*)fs, b = *(const f32x4*)(fs + 4); v4u o; o.x = pk2(a[0], a[1]); o.y = pk2(a[2], a[3]); o.z = pk2(b[0], b[1]); o.w = pk2(b[2], b[3]); pre[i] = o; }
.LBB0_514:
	s_mov_b32 s98, 0
	s_add_i32 s18, s2, 2
	s_mov_b64 s[10:11], 0x58000
	s_cmp_gt_u32 s2, 5
	s_mov_b32 s3, 0
	v_mov_b64_e32 v[12:13], v[178:179]
	v_mov_b64_e32 v[14:15], v[180:181]
	s_mov_b64 s[12:13], -1
	s_cbranch_scc1 .LBB0_518
	s_min_i32 s3, s18, 8
	s_and_b64 vcc, exec, s[34:35]
	s_cbranch_vccz .LBB0_517
	s_lshl_b32 s10, s3, 6
	s_waitcnt vmcnt(1)
	v_add_u32_e32 v4, s10, v170
	v_ashrrev_i32_e32 v5, 31, v4
	v_lshlrev_b64 v[4:5], 11, v[4:5]
	v_lshl_add_u64 v[6:7], v[182:183], 0, v[4:5]
	v_lshl_add_u64 v[6:7], v[6:7], 0, s[40:41]
	v_lshl_add_u64 v[4:5], v[184:185], 0, v[4:5]
	v_cndmask_b32_e64 v5, v7, v5, s[4:5]
	v_cndmask_b32_e64 v4, v6, v4, s[4:5]
	global_load_dwordx4 v[224:227], v[4:5], off offset:16
	global_load_dwordx4 v[4:7], v[4:5], off
	v_add_u32_e32 v8, s10, v172
	v_ashrrev_i32_e32 v9, 31, v8
	v_lshlrev_b64 v[8:9], 11, v[8:9]
	v_lshl_add_u64 v[10:11], v[188:189], 0, v[8:9]
	v_lshl_add_u64 v[8:9], v[186:187], 0, v[8:9]
	v_lshl_add_u64 v[8:9], v[8:9], 0, s[40:41]
	v_cndmask_b32_e64 v9, v9, v11, s[6:7]
	v_cndmask_b32_e64 v8, v8, v10, s[6:7]
	global_load_dwordx2 v[228:229], v[8:9], off offset:16
	global_load_dwordx2 v[238:239], v[8:9], off offset:24
	global_load_dwordx4 v[8:11], v[8:9], off
	s_mov_b32 s98, 1

; #define LAS __attribute__((address_space(3)))
; __device__ __forceinline__ unsigned pk2(float lo, float hi) { f32x2_t v = {lo, hi}; bf16x2_t b = __builtin_convertvector(v, bf16x2_t); return __builtin_bit_cast(unsigned, b); }
; template <int MODE> __device__ __forceinline__ void tile_loads(const AU& U, const TL& C, int T, v4u (&pre)[3]) {
;     ...
;             const float* fs = cc < 8 ? U.kAf + (size_t)(T * 64 + row) * U.pA + cc * 8 : U.vAf + (size_t)(T * 64 + row) * U.pA + (cc - 8) * 8;
;             const f32x4 a = *(const f32x4*)fs, b = *(const f32x4*)(fs + 4); v4u o; o.x = pk2(a[0], a[1]); o.y = pk2(a[2], a[3]); o.z = pk2(b[0], b[1]); o.w = pk2(b[2], b[3]); pre[i] = o; }
; template <int MODE> __device__ __forceinline__ void tile_stores(LAS unsigned char* buf, const TL& C, const v4u (&pre)[3]) {
;     constexpr int NLD = ((MODE == 0 ? 20 : 16) * 64 + 511) / 512;
; #pragma unroll
;     for (int i = 0; i < NLD; ++i) *(LAS v4u*)(buf + C.ld[i]) = pre[i];
; }
.LBB0_536:
	s_cmp_eq_u32 s99, 0
	s_cbranch_scc1 .Lbs_b_ok
	s_waitcnt vmcnt(0)
	v_cvt_pk_bf16_f32 v130, v130, v131
	v_cvt_pk_bf16_f32 v131, v132, v133
	v_cvt_pk_bf16_f32 v132, v240, v241
	v_cvt_pk_bf16_f32 v133, v242, v243
	v_cvt_pk_bf16_f32 v134, v134, v135
	v_cvt_pk_bf16_f32 v135, v136, v137
	v_cvt_pk_bf16_f32 v136, v244, v245
	v_cvt_pk_bf16_f32 v137, v246, v247

; __device__ __forceinline__ unsigned pk2(float lo, float hi) { f32x2_t v = {lo, hi}; bf16x2_t b = __builtin_convertvector(v, bf16x2_t); return __builtin_bit_cast(unsigned, b); }
; template <int MODE> __device__ __forceinline__ void tile_loads(const AU& U, const TL& C, int T, v4u (&pre)[3]) {
;     constexpr int CPR = MODE == 0 ? 20 : 16, NCH = 64 * CPR, NLD = (NCH + 511) / 512;
;     const bool useA = T < U.ntA;
;     if (MODE != 0 && useA && U.kAf) {
; #pragma unroll
;         for (int i = 0; i < NLD; ++i) { const int row = C.c[i] / CPR, cc = C.c[i] % CPR;
;             const float* fs = cc < 8 ? U.kAf + (size_t)(T * 64 + row) * U.pA + cc * 8 : U.vAf + (size_t)(T * 64 + row) * U.pA + (cc - 8) * 8;
;             const f32x4 a = *(const f32x4*)fs, b = *(const f32x4*)(fs + 4); v4u o; o.x = pk2(a[0], a[1]); o.y = pk2(a[2], a[3]); o.z = pk2(b[0], b[1]); o.w = pk2(b[2], b[3]); pre[i] = o; }
.LBB0_537:
	s_waitcnt lgkmcnt(0)
	s_barrier
	s_andn2_b64 vcc, exec, s[10:11]
	s_mov_b64 s[10:11], -1
	s_cbranch_vccnz .LBB0_513
	s_mov_b32 s99, 0
	s_cmp_gt_u32 s2, 4
	s_cbranch_scc1 .LBB0_542
	s_min_u32 s3, s2, 5
	s_add_i32 s3, s3, 3
	s_and_b64 vcc, exec, s[34:35]
	s_cbranch_vccz .LBB0_541
	s_lshl_b32 s10, s3, 6
	v_add_u32_e32 v12, s10, v170
	v_ashrrev_i32_e32 v13, 31, v12
	v_lshlrev_b64 v[12:13], 11, v[12:13]
	v_lshl_add_u64 v[14:15], v[182:183], 0, v[12:13]
	v_lshl_add_u64 v[14:15], v[14:15], 0, s[40:41]
	v_lshl_add_u64 v[12:13], v[184:185], 0, v[12:13]
	v_cndmask_b32_e64 v17, v15, v13, s[4:5]
	v_cndmask_b32_e64 v16, v14, v12, s[4:5]
	global_load_dwordx4 v[240:243], v[16:17], off offset:16
	global_load_dwordx4 v[130:133], v[16:17], off
	v_add_u32_e32 v12, s10, v172
	v_ashrrev_i32_e32 v13, 31, v12
	v_lshlrev_b64 v[12:13], 11, v[12:13]
	v_lshl_add_u64 v[14:15], v[188:189], 0, v[12:13]
	v_lshl_add_u64 v[12:13], v[186:187], 0, v[12:13]
	v_lshl_add_u64 v[12:13], v[12:13], 0, s[40:41]
	v_cndmask_b32_e64 v17, v13, v15, s[6:7]
	v_cndmask_b32_e64 v16, v12, v14, s[6:7]
	global_load_dwordx4 v[244:247], v[16:17], off offset:16
	global_load_dwordx4 v[134:137], v[16:17], off
	s_mov_b32 s99, 1

; #define LAS __attribute__((address_space(3)))
; __device__ __forceinline__ unsigned pk2(float lo, float hi) { f32x2_t v = {lo, hi}; bf16x2_t b = __builtin_convertvector(v, bf16x2_t); return __builtin_bit_cast(unsigned, b); }
; template <bool SMP> __device__ __forceinline__ void sb_loads(const bf16* Hb, const float* c_sk, const float* c_sv, int b, int c, int hg, int T, int tid, v4u (&pre)[8]) {
;     ...
;         for (int hf = 0; hf < 2; ++hf) {
; #pragma unroll
;             for (int i2 = 0; i2 < 4; ++i2) { const int i = hf * 4 + i2; const int ch = tid + 512 * i, row = ch >> 6, cc = ch & 63;
;                 const float* fs = (cc >= 32 ? c_sv : c_sk) + ((size_t)b * PAST + (size_t)T * 64 + row) * 1024 + hg * 256 + (cc & 31) * 8;
;                 const f32x4 a = *(const f32x4*)fs, bq = *(const f32x4*)(fs + 4); v4u o; o.x = pk2(a[0], a[1]); o.y = pk2(a[2], a[3]); o.z = pk2(bq[0], bq[1]); o.w = pk2(bq[2], bq[3]); pre[i] = o; }
;             asm volatile("" ::: "memory"); } }
; }
; __device__ __forceinline__ void sb_stores(LAS unsigned char* lds, int tid, const v4u (&pre)[8]) {
; #pragma unroll
;     for (int i = 0; i < 8; ++i) { const int ch = tid + 512 * i, row = ch >> 6, cc = ch & 63;
;         *(LAS v4u*)(lds + ((cc & 31) >> 3) * SB_HB + (cc >= 32 ? 9216 : 0) + row * 144 + (cc & 7) * 16) = pre[i]; }
; template <bool SMP> __device__ __forceinline__ void sb_unit4(const bf16* Hb, const float* c_sk, const float* c_sv, bf16* O, int b, int c, int hg, LAS unsigned char* lds) {
;     ...
;     for (int T = tq;; --T) {
;         sb_stores(lds, tid, pre);
;         __syncthreads();
;         const bool has_next = T > 0;
;         if (has_next) sb_loads<SMP>(Hb, c_sk, c_sv, b, c, hg, T - 1, tid, pre);
.LBB0_1350:
	s_cmpk_lg_i32 s3, 0xfc00
	s_cselect_b64 s[76:77], -1, 0
	s_cmpk_eq_i32 s3, 0xfc00
	s_waitcnt vmcnt(7)
	ds_write_b128 v209, v[90:93]
	s_waitcnt vmcnt(6)
	ds_write_b128 v213, v[94:97]
	s_waitcnt vmcnt(5)
	ds_write_b128 v214, v[98:101]
	s_waitcnt vmcnt(4)
	ds_write_b128 v215, v[102:105]
	s_waitcnt vmcnt(3)
	ds_write_b128 v216, v[106:109]
	s_waitcnt vmcnt(2)
	ds_write_b128 v217, v[110:113]
	s_waitcnt vmcnt(1)
	ds_write_b128 v218, v[114:117]
	s_waitcnt vmcnt(0)
	ds_write_b128 v219, v[118:121]
	s_waitcnt lgkmcnt(0)
	s_barrier
	s_cbranch_scc1 .LBB0_1352
	s_add_i32 s84, s2, s3
	v_lshl_add_u64 v[32:33], s[84:85], 0, v[156:157]
	v_lshlrev_b64 v[32:33], 12, v[32:33]
	v_lshl_add_u64 v[36:37], v[172:173], 0, v[32:33]
	global_load_dwordx4 v[42:45], v[36:37], off offset:16
	global_load_dwordx4 v[90:93], v[36:37], off
	v_lshl_add_u64 v[32:33], s[84:85], 0, v[158:159]
	v_lshlrev_b64 v[32:33], 12, v[32:33]
	v_lshl_add_u64 v[36:37], v[172:173], 0, v[32:33]
	global_load_dwordx4 v[46:49], v[36:37], off offset:16
	global_load_dwordx4 v[94:97], v[36:37], off
	v_lshl_add_u64 v[32:33], s[84:85], 0, v[160:161]
	v_lshlrev_b64 v[32:33], 12, v[32:33]
	v_lshl_add_u64 v[36:37], v[172:173], 0, v[32:33]
	global_load_dwordx4 v[50:53], v[36:37], off offset:16
	global_load_dwordx4 v[98:101], v[36:37], off
	v_lshl_add_u64 v[32:33], s[84:85], 0, v[162:163]
	v_lshlrev_b64 v[32:33], 12, v[32:33]
	v_lshl_add_u64 v[36:37], v[172:173], 0, v[32:33]
	global_load_dwordx4 v[54:57], v[36:37], off offset:16
	global_load_dwordx4 v[102:105], v[36:37], off
	v_lshl_add_u64 v[32:33], s[84:85], 0, v[164:165]
	v_lshlrev_b64 v[32:33], 12, v[32:33]
	v_lshl_add_u64 v[36:37], v[172:173], 0, v[32:33]
	global_load_dwordx4 v[58:61], v[36:37], off offset:16
	global_load_dwordx4 v[106:109], v[36:37], off
	v_lshl_add_u64 v[32:33], s[84:85], 0, v[166:167]
	v_lshlrev_b64 v[32:33], 12, v[32:33]
	v_lshl_add_u64 v[36:37], v[172:173], 0, v[32:33]
	global_load_dwordx4 v[62:65], v[36:37], off offset:16
	global_load_dwordx4 v[110:113], v[36:37], off
	v_lshl_add_u64 v[32:33], s[84:85], 0, v[168:169]
	v_lshlrev_b64 v[32:33], 12, v[32:33]
	v_lshl_add_u64 v[36:37], v[172:173], 0, v[32:33]
	global_load_dwordx4 v[66:69], v[36:37], off offset:16
	global_load_dwordx4 v[114:117], v[36:37], off
	v_lshl_add_u64 v[32:33], s[84:85], 0, v[170:171]
	v_lshlrev_b64 v[32:33], 12, v[32:33]
	v_lshl_add_u64 v[36:37], v[172:173], 0, v[32:33]
	global_load_dwordx4 v[70:73], v[36:37], off offset:16
	global_load_dwordx4 v[118:121], v[36:37], off
	s_waitcnt vmcnt(14)
	v_cvt_pk_bf16_f32 v90, v90, v91
	v_cvt_pk_bf16_f32 v91, v92, v93
	v_cvt_pk_bf16_f32 v92, v42, v43
	v_cvt_pk_bf16_f32 v93, v44, v45
	s_waitcnt vmcnt(12)
	v_cvt_pk_bf16_f32 v94, v94, v95
	v_cvt_pk_bf16_f32 v95, v96, v97
	v_cvt_pk_bf16_f32 v96, v46, v47
	v_cvt_pk_bf16_f32 v97, v48, v49
	s_waitcnt vmcnt(10)
	v_cvt_pk_bf16_f32 v98, v98, v99
	v_cvt_pk_bf16_f32 v99, v100, v101
	v_cvt_pk_bf16_f32 v100, v50, v51
	v_cvt_pk_bf16_f32 v101, v52, v53
	s_waitcnt vmcnt(8)
	v_cvt_pk_bf16_f32 v102, v102, v103
	v_cvt_pk_bf16_f32 v103, v104, v105
	v_cvt_pk_bf16_f32 v104, v54, v55
	v_cvt_pk_bf16_f32 v105, v56, v57
	s_waitcnt vmcnt(6)
	v_cvt_pk_bf16_f32 v106, v106, v107
	v_cvt_pk_bf16_f32 v107, v108, v109
	v_cvt_pk_bf16_f32 v108, v58, v59
	v_cvt_pk_bf16_f32 v109, v60, v61
	s_waitcnt vmcnt(4)
	v_cvt_pk_bf16_f32 v110, v110, v111
	v_cvt_pk_bf16_f32 v111, v112, v113
	v_cvt_pk_bf16_f32 v112, v62, v63
	v_cvt_pk_bf16_f32 v113, v64, v65
	s_waitcnt vmcnt(2)
	v_cvt_pk_bf16_f32 v114, v114, v115
	v_cvt_pk_bf16_f32 v115, v116, v117
	v_cvt_pk_bf16_f32 v116, v66, v67
	v_cvt_pk_bf16_f32 v117, v68, v69
	s_waitcnt vmcnt(0)
	v_cvt_pk_bf16_f32 v118, v118, v119
	v_cvt_pk_bf16_f32 v119, v120, v121
	v_cvt_pk_bf16_f32 v120, v70, v71
	v_cvt_pk_bf16_f32 v121, v72, v73
